# MLA body B (waves 4-7): P packs first, row-sum add chain moved into the PV MFMA shadows, tile loads issued after the sum chain; copy-movs removed in both bodies
# baseline (speedup 1.0000x reference)
; template <int DQK> __device__ __forceinline__ void partialSM(f32x16& p0, f32x16& p1, float& m_reg, float& mn, float& alpha) {
;     ...
;   float pmax = p0[0];
; #pragma unroll
;   for (int r = 1; r < 16; ++r) pmax = fmaxf(pmax, p0[r]);
; #pragma unroll
;   for (int r = 0; r < 16; ++r) pmax = fmaxf(pmax, p1[r]);
;   { auto rr = __builtin_amdgcn_permlane32_swap(__float_as_uint(pmax), __float_as_uint(pmax), false, false);
;     pmax = fmaxf(__uint_as_float(rr[0]), __uint_as_float(rr[1])); }
;   if (__builtin_expect(__all(pmax - m_reg <= THR / SCALE), 1)) { mn = m_reg; alpha = 1.f; }
;   else { mn = fmaxf(m_reg, pmax); alpha = __builtin_amdgcn_exp2f((m_reg - mn) * C); m_reg = mn; }
;   float mnC = -mn * C;
; #pragma unroll
;   for (int r = 0; r < 16; ++r) p0[r] = fmaf(p0[r], C, mnC);
; #pragma unroll
;   for (int r = 0; r < 16; ++r) p1[r] = fmaf(p1[r], C, mnC);
; #pragma unroll
;   for (int r = 0; r < 16; ++r) p0[r] = __builtin_amdgcn_exp2f(p0[r]);
; }
; __device__ __forceinline__ void finishSM(f32x16& p0, f32x16& p1, float alpha, float& l_reg, bf16x8& pa0, bf16x8& pa1, bf16x8& pa2, bf16x8& pa3) {
; #pragma unroll
;   for (int r = 0; r < 16; ++r) p1[r] = __builtin_amdgcn_exp2f(p1[r]);
;   float ps = 0;
; #pragma unroll
;   for (int r = 0; r < 16; ++r) ps += p0[r];
; #pragma unroll
;   for (int r = 0; r < 16; ++r) ps += p1[r];
;   { auto rr = __builtin_amdgcn_permlane32_swap(__float_as_uint(ps), __float_as_uint(ps), false, false);
;     ps = __uint_as_float(rr[0]) + __uint_as_float(rr[1]); }
;   l_reg = l_reg * alpha + ps;
;     ...
;   PK4(p0, 0, pa0); PK4(p0, 8, pa1); PK4(p1, 0, pa2); PK4(p1, 8, pa3);
;     ...
; }
; template <int DQK> __device__ __forceinline__ void qkt(f32x16& p0, f32x16& p1, const char* Ks, const bf16x8* qr, int r32, int hi) {
;   p0 = f32x16{}; p1 = f32x16{};
; #pragma unroll
;   for (int d0 = 0; d0 < DQK / 16; ++d0) { int cb = (d0 * 16 + hi * 8) * 2;
;     bf16x8 b0 = *reinterpret_cast<const bf16x8*>(Ks + KSWZ(r32, cb));
;     bf16x8 b1 = *reinterpret_cast<const bf16x8*>(Ks + KSWZ(32 + r32, cb));
;     p0 = __builtin_amdgcn_mfma_f32_32x32x16_bf16(b0, qr[d0], p0, 0, 0, 0);
;     p1 = __builtin_amdgcn_mfma_f32_32x32x16_bf16(b1, qr[d0], p1, 0, 0, 0); }
; }
; __device__ __forceinline__ int v_st(int k, int c) { const int kk = (k & ~0xC) | ((k & 4) << 1) | ((k & 8) >> 1); return ((kk >> 3) * 4 + (c >> 5)) * 512 + ((kk & 7) * 32 + (c & 31)) * 2; }
.LBB0_300:
	s_add_i32 s25, s11, -3
	s_cmp_lg_u32 s32, 0
	s_cbranch_scc1 .Lmy_h1B
	ds_read_b128 v[32:35], v148 offset:49152
	ds_read_b128 v[36:39], v148 offset:57344
	ds_read_b128 v[164:167], v152 offset:49152
	ds_read_b128 v[168:171], v152 offset:57344
	s_waitcnt lgkmcnt(3)
	v_mfma_f32_32x32x16_bf16 v[48:63], v[32:35], v[84:87], v[210:225]
	s_waitcnt lgkmcnt(2)
	v_mfma_f32_32x32x16_bf16 v[32:47], v[36:39], v[84:87], v[210:225]
	s_waitcnt lgkmcnt(1)
	v_mfma_f32_32x32x16_bf16 v[48:63], v[164:167], v[80:83], v[48:63]
	s_waitcnt lgkmcnt(0)
	v_mfma_f32_32x32x16_bf16 v[32:47], v[168:171], v[80:83], v[32:47]
	ds_read_b128 v[164:167], v151 offset:49152
	ds_read_b128 v[168:171], v151 offset:57344
	s_waitcnt lgkmcnt(1)
	v_mfma_f32_32x32x16_bf16 v[48:63], v[164:167], v[76:79], v[48:63]
	s_waitcnt lgkmcnt(0)
	v_mfma_f32_32x32x16_bf16 v[32:47], v[168:171], v[76:79], v[32:47]
	ds_read_b128 v[164:167], v149 offset:49152
	ds_read_b128 v[168:171], v149 offset:57344
	s_waitcnt lgkmcnt(1)
	v_mfma_f32_32x32x16_bf16 v[48:63], v[164:167], v[72:75], v[48:63]
	s_waitcnt lgkmcnt(0)
	v_mfma_f32_32x32x16_bf16 v[32:47], v[168:171], v[72:75], v[32:47]
	ds_read_b128 v[164:167], v150 offset:49152
	ds_read_b128 v[168:171], v150 offset:57344
	s_waitcnt lgkmcnt(1)
	v_mfma_f32_32x32x16_bf16 v[48:63], v[164:167], v[68:71], v[48:63]
	s_waitcnt lgkmcnt(0)
	v_mfma_f32_32x32x16_bf16 v[32:47], v[168:171], v[68:71], v[32:47]
	ds_read_b128 v[164:167], v153 offset:49152
	ds_read_b128 v[168:171], v153 offset:57344
	s_waitcnt vmcnt(0)
	ds_write_b128 v146, v[88:91] offset:32768
	ds_write_b128 v147, v[96:99] offset:32768
	ds_write_b128 v145, v[92:95] offset:16384
	s_waitcnt lgkmcnt(4)
	v_mfma_f32_32x32x16_bf16 v[48:63], v[164:167], v[64:67], v[48:63]
	s_waitcnt lgkmcnt(3)
	v_mfma_f32_32x32x16_bf16 v[32:47], v[168:171], v[64:67], v[32:47]
	ds_read_b64_tr_b16 v[184:185], v144 offset:0
	ds_read_b64_tr_b16 v[186:187], v144 offset:0x800
	ds_read_b64_tr_b16 v[188:189], v144 offset:0x1000
	ds_read_b64_tr_b16 v[190:191], v144 offset:0x1800
	ds_read_b64_tr_b16 v[192:193], v144 offset:0x2000
	ds_read_b64_tr_b16 v[194:195], v144 offset:0x2800
	ds_read_b64_tr_b16 v[196:197], v144 offset:0x3000
	ds_read_b64_tr_b16 v[198:199], v144 offset:0x3800
	v_cvt_pk_bf16_f32 v200, v126, v160
	v_cvt_pk_bf16_f32 v201, v127, v161
	v_cvt_pk_bf16_f32 v202, v158, v162
	v_cvt_pk_bf16_f32 v203, v159, v163
	v_cvt_pk_bf16_f32 v226, v118, v121
	v_cvt_pk_bf16_f32 v227, v119, v122
	v_cvt_pk_bf16_f32 v228, v120, v123
	v_cvt_pk_bf16_f32 v229, v124, v125
	v_cvt_pk_bf16_f32 v230, v114, v115
	v_cvt_pk_bf16_f32 v231, v112, v113
	v_cvt_pk_bf16_f32 v232, v108, v109
	v_cvt_pk_bf16_f32 v233, v104, v105
	v_cvt_pk_bf16_f32 v136, v102, v103
	v_cvt_pk_bf16_f32 v137, v110, v111
	v_cvt_pk_bf16_f32 v138, v106, v107
	v_cvt_pk_bf16_f32 v139, v100, v101
	v_add_f32_e32 v155, v126, v160
	v_add_f32_e32 v155, v127, v155
	v_add_f32_e32 v155, v161, v155
	v_add_f32_e32 v155, v158, v155
	v_add_f32_e32 v155, v162, v155
	v_add_f32_e32 v155, v159, v155
	v_add_f32_e32 v155, v163, v155
	v_add_f32_e32 v155, v118, v155
	v_add_f32_e32 v155, v121, v155
	v_add_f32_e32 v155, v119, v155
	v_add_f32_e32 v155, v122, v155
	v_add_f32_e32 v155, v120, v155
	v_add_f32_e32 v155, v123, v155
	v_add_f32_e32 v155, v124, v155
	v_add_f32_e32 v155, v125, v155
	v_add_f32_e32 v155, v114, v155
	v_add_f32_e32 v155, v115, v155
	v_add_f32_e32 v155, v112, v155
	v_add_f32_e32 v155, v113, v155
	v_add_f32_e32 v155, v108, v155
	v_add_f32_e32 v155, v109, v155
	v_add_f32_e32 v155, v104, v155
	v_add_f32_e32 v155, v105, v155
	v_add_f32_e32 v155, v102, v155
	v_add_f32_e32 v155, v103, v155
	v_add_f32_e32 v155, v110, v155
	v_add_f32_e32 v155, v111, v155
	v_add_f32_e32 v155, v106, v155
	v_add_f32_e32 v155, v107, v155
	v_add_f32_e32 v155, v100, v155
	v_add_f32_e32 v155, v101, v155
	s_lshl_b32 s0, s11, 6
	s_cmpk_lt_u32 s25, 0x7e
	s_cselect_b32 s1, s10, s24
	s_add_i32 s1, s1, s0
	s_addk_i32 s1, 0xffc0
	s_mul_i32 s1, s1, 0x300
	s_add_u32 s12, s18, s1
	s_addc_u32 s13, s19, 0
	s_cmpk_lt_u32 s25, 0x7f
	s_cselect_b32 s98, s10, s24
	s_add_i32 s98, s98, s0
	s_addk_i32 s98, 0xff80
	s_lshl_b32 s98, s98, 9
	s_add_u32 s98, s20, s98
	s_addc_u32 s99, s21, 0
	global_load_dwordx4 v[100:103], v134, s[12:13]
	global_load_dwordx4 v[108:111], v135, s[98:99]
	global_load_dwordx4 v[104:107], v238, s[12:13] offset:128
	s_waitcnt lgkmcnt(0)
	s_nop 0
	v_mfma_f32_32x32x16_bf16 v[0:15], v[200:203], v[184:187], v[0:15]
	ds_read_b64_tr_b16 v[184:185], v144 offset:0x200
	ds_read_b64_tr_b16 v[186:187], v144 offset:0xa00
	v_max_f32_e32 v112, v48, v49
	v_max3_f32 v112, v112, v50, v51
	v_max3_f32 v112, v112, v52, v53
	v_max3_f32 v112, v112, v54, v55
	v_max3_f32 v112, v112, v56, v57
	v_mfma_f32_32x32x16_bf16 v[0:15], v[226:229], v[188:191], v[0:15]
	ds_read_b64_tr_b16 v[188:189], v144 offset:0x1200
	ds_read_b64_tr_b16 v[190:191], v144 offset:0x1a00
	v_max3_f32 v112, v112, v58, v59
	v_max3_f32 v112, v112, v60, v61
	v_max3_f32 v112, v112, v62, v63
	v_max3_f32 v112, v112, v32, v33
	v_max3_f32 v112, v112, v34, v35
	v_mfma_f32_32x32x16_bf16 v[0:15], v[230:233], v[192:195], v[0:15]
	ds_read_b64_tr_b16 v[192:193], v144 offset:0x2200
	ds_read_b64_tr_b16 v[194:195], v144 offset:0x2a00
	v_max3_f32 v112, v112, v36, v37
	v_max3_f32 v112, v112, v38, v39
	v_max3_f32 v112, v112, v40, v41
	v_max3_f32 v112, v112, v42, v43
	v_max3_f32 v112, v112, v44, v45
	v_mfma_f32_32x32x16_bf16 v[0:15], v[136:139], v[196:199], v[0:15]
	ds_read_b64_tr_b16 v[196:197], v144 offset:0x3200
	ds_read_b64_tr_b16 v[198:199], v144 offset:0x3a00
	v_max3_f32 v112, v112, v46, v47
	v_cmp_ge_f32_e32 vcc, s80, v112
	s_cmp_eq_u64 vcc, exec
	s_cbranch_scc0 .Lmy_rare_a1
	v_mov_b32_e32 v157, 1.0
	s_mov_b64 vcc, 0

; template <int DQK> __device__ __forceinline__ void partialSM(f32x16& p0, f32x16& p1, float& m_reg, float& mn, float& alpha) {
;     ...
;   float pmax = p0[0];
; #pragma unroll
;   for (int r = 1; r < 16; ++r) pmax = fmaxf(pmax, p0[r]);
; #pragma unroll
;   for (int r = 0; r < 16; ++r) pmax = fmaxf(pmax, p1[r]);
;   { auto rr = __builtin_amdgcn_permlane32_swap(__float_as_uint(pmax), __float_as_uint(pmax), false, false);
;     pmax = fmaxf(__uint_as_float(rr[0]), __uint_as_float(rr[1])); }
;   if (__builtin_expect(__all(pmax - m_reg <= THR / SCALE), 1)) { mn = m_reg; alpha = 1.f; }
;   else { mn = fmaxf(m_reg, pmax); alpha = __builtin_amdgcn_exp2f((m_reg - mn) * C); m_reg = mn; }
;   float mnC = -mn * C;
; #pragma unroll
;   for (int r = 0; r < 16; ++r) p0[r] = fmaf(p0[r], C, mnC);
; #pragma unroll
;   for (int r = 0; r < 16; ++r) p1[r] = fmaf(p1[r], C, mnC);
; #pragma unroll
;   for (int r = 0; r < 16; ++r) p0[r] = __builtin_amdgcn_exp2f(p0[r]);
; }
; __device__ __forceinline__ void finishSM(f32x16& p0, f32x16& p1, float alpha, float& l_reg, bf16x8& pa0, bf16x8& pa1, bf16x8& pa2, bf16x8& pa3) {
; #pragma unroll
;   for (int r = 0; r < 16; ++r) p1[r] = __builtin_amdgcn_exp2f(p1[r]);
;   float ps = 0;
; #pragma unroll
;   for (int r = 0; r < 16; ++r) ps += p0[r];
; #pragma unroll
;   for (int r = 0; r < 16; ++r) ps += p1[r];
;   { auto rr = __builtin_amdgcn_permlane32_swap(__float_as_uint(ps), __float_as_uint(ps), false, false);
;     ps = __uint_as_float(rr[0]) + __uint_as_float(rr[1]); }
;   l_reg = l_reg * alpha + ps;
;     ...
;   PK4(p0, 0, pa0); PK4(p0, 8, pa1); PK4(p1, 0, pa2); PK4(p1, 8, pa3);
;     ...
; }
; template <int DQK> __device__ __forceinline__ void qkt(f32x16& p0, f32x16& p1, const char* Ks, const bf16x8* qr, int r32, int hi) {
;   p0 = f32x16{}; p1 = f32x16{};
; #pragma unroll
;   for (int d0 = 0; d0 < DQK / 16; ++d0) { int cb = (d0 * 16 + hi * 8) * 2;
;     bf16x8 b0 = *reinterpret_cast<const bf16x8*>(Ks + KSWZ(r32, cb));
;     bf16x8 b1 = *reinterpret_cast<const bf16x8*>(Ks + KSWZ(32 + r32, cb));
;     p0 = __builtin_amdgcn_mfma_f32_32x32x16_bf16(b0, qr[d0], p0, 0, 0, 0);
;     p1 = __builtin_amdgcn_mfma_f32_32x32x16_bf16(b1, qr[d0], p1, 0, 0, 0); }
; }
; __device__ __forceinline__ int v_st(int k, int c) { const int kk = (k & ~0xC) | ((k & 4) << 1) | ((k & 8) >> 1); return ((kk >> 3) * 4 + (c >> 5)) * 512 + ((kk & 7) * 32 + (c & 31)) * 2; }
.LBB0_304:
	s_waitcnt lgkmcnt(0)
	s_barrier
	ds_read_b128 v[32:35], v148 offset:32768
	ds_read_b128 v[36:39], v148 offset:40960
	ds_read_b128 v[176:179], v152 offset:32768
	ds_read_b128 v[180:183], v152 offset:40960
	s_waitcnt lgkmcnt(3)
	v_mfma_f32_32x32x16_bf16 v[48:63], v[32:35], v[84:87], v[210:225]
	s_waitcnt lgkmcnt(2)
	v_mfma_f32_32x32x16_bf16 v[32:47], v[36:39], v[84:87], v[210:225]
	s_waitcnt lgkmcnt(1)
	v_mfma_f32_32x32x16_bf16 v[48:63], v[176:179], v[80:83], v[48:63]
	s_waitcnt lgkmcnt(0)
	v_mfma_f32_32x32x16_bf16 v[32:47], v[180:183], v[80:83], v[32:47]
	ds_read_b128 v[176:179], v151 offset:32768
	ds_read_b128 v[180:183], v151 offset:40960
	s_waitcnt lgkmcnt(1)
	v_mfma_f32_32x32x16_bf16 v[48:63], v[176:179], v[76:79], v[48:63]
	s_waitcnt lgkmcnt(0)
	v_mfma_f32_32x32x16_bf16 v[32:47], v[180:183], v[76:79], v[32:47]
	ds_read_b128 v[176:179], v149 offset:32768
	ds_read_b128 v[180:183], v149 offset:40960
	s_waitcnt lgkmcnt(1)
	v_mfma_f32_32x32x16_bf16 v[48:63], v[176:179], v[72:75], v[48:63]
	s_waitcnt lgkmcnt(0)
	v_mfma_f32_32x32x16_bf16 v[32:47], v[180:183], v[72:75], v[32:47]
	ds_read_b128 v[176:179], v150 offset:32768
	ds_read_b128 v[180:183], v150 offset:40960
	s_waitcnt lgkmcnt(1)
	v_mfma_f32_32x32x16_bf16 v[48:63], v[176:179], v[68:71], v[48:63]
	s_waitcnt lgkmcnt(0)
	v_mfma_f32_32x32x16_bf16 v[32:47], v[180:183], v[68:71], v[32:47]
	ds_read_b128 v[176:179], v153 offset:32768
	ds_read_b128 v[180:183], v153 offset:40960
	s_waitcnt vmcnt(0)
	ds_write_b128 v146, v[100:103] offset:49152
	ds_write_b128 v147, v[104:107] offset:49152
	ds_write_b128 v145, v[108:111]
	s_waitcnt lgkmcnt(4)
	v_mfma_f32_32x32x16_bf16 v[48:63], v[176:179], v[64:67], v[48:63]
	s_waitcnt lgkmcnt(3)
	v_mfma_f32_32x32x16_bf16 v[32:47], v[180:183], v[64:67], v[32:47]
	ds_read_b64_tr_b16 v[184:185], v143 offset:0
	ds_read_b64_tr_b16 v[186:187], v143 offset:0x800
	ds_read_b64_tr_b16 v[188:189], v143 offset:0x1000
	ds_read_b64_tr_b16 v[190:191], v143 offset:0x1800
	ds_read_b64_tr_b16 v[192:193], v143 offset:0x2000
	ds_read_b64_tr_b16 v[194:195], v143 offset:0x2800
	ds_read_b64_tr_b16 v[196:197], v143 offset:0x3000
	ds_read_b64_tr_b16 v[198:199], v143 offset:0x3800
	v_cvt_pk_bf16_f32 v200, v112, v127
	v_cvt_pk_bf16_f32 v201, v113, v126
	v_cvt_pk_bf16_f32 v202, v114, v125
	v_cvt_pk_bf16_f32 v203, v115, v124
	v_cvt_pk_bf16_f32 v226, v116, v123
	v_cvt_pk_bf16_f32 v227, v117, v122
	v_cvt_pk_bf16_f32 v228, v118, v121
	v_cvt_pk_bf16_f32 v229, v119, v120
	v_cvt_pk_bf16_f32 v230, v167, v168
	v_cvt_pk_bf16_f32 v231, v169, v170
	v_cvt_pk_bf16_f32 v232, v171, v172
	v_cvt_pk_bf16_f32 v233, v160, v161
	v_cvt_pk_bf16_f32 v136, v162, v163
	v_cvt_pk_bf16_f32 v137, v164, v165
	v_cvt_pk_bf16_f32 v138, v166, v173
	v_cvt_pk_bf16_f32 v139, v174, v159
	v_add_f32_e32 v156, v112, v127
	v_add_f32_e32 v156, v113, v156
	v_add_f32_e32 v156, v126, v156
	v_add_f32_e32 v156, v114, v156
	v_add_f32_e32 v156, v125, v156
	v_add_f32_e32 v156, v115, v156
	v_add_f32_e32 v156, v124, v156
	v_add_f32_e32 v156, v116, v156
	v_add_f32_e32 v156, v123, v156
	v_add_f32_e32 v156, v117, v156
	v_add_f32_e32 v156, v122, v156
	v_add_f32_e32 v156, v118, v156
	v_add_f32_e32 v156, v121, v156
	v_add_f32_e32 v156, v119, v156
	v_add_f32_e32 v156, v120, v156
	v_add_f32_e32 v156, v167, v156
	v_add_f32_e32 v156, v168, v156
	v_add_f32_e32 v156, v169, v156
	v_add_f32_e32 v156, v170, v156
	v_add_f32_e32 v156, v171, v156
	v_add_f32_e32 v156, v172, v156
	v_add_f32_e32 v156, v160, v156
	v_add_f32_e32 v156, v161, v156
	v_add_f32_e32 v156, v162, v156
	v_add_f32_e32 v156, v163, v156
	v_add_f32_e32 v156, v164, v156
	v_add_f32_e32 v156, v165, v156
	v_add_f32_e32 v156, v166, v156
	v_add_f32_e32 v156, v173, v156
	v_add_f32_e32 v156, v174, v156
	v_add_f32_e32 v156, v159, v156
	s_lshl_b32 s0, s11, 6
	s_cmpk_lt_u32 s25, 0x7e
	s_cselect_b32 s98, s10, s24
	s_add_i32 s98, s98, s0
	s_addk_i32 s98, 0xffc0
	s_lshl_b32 s98, s98, 9
	s_add_u32 s98, s20, s98
	s_addc_u32 s99, s21, 0
	global_load_dwordx4 v[92:95], v135, s[98:99]
	s_cmpk_gt_u32 s25, 0x80
	s_cbranch_scc1 .LBB0_306
	s_cmpk_lt_u32 s25, 0x7d
	s_cselect_b32 s1, s10, s24
	s_add_i32 s1, s1, s0
	s_mul_i32 s1, s1, 0x300
	s_add_u32 s12, s18, s1
	s_addc_u32 s13, s19, 0
	global_load_dwordx4 v[88:91], v134, s[12:13]
	global_load_dwordx4 v[96:99], v238, s[12:13] offset:128

; __device__ __forceinline__ void finishSM(f32x16& p0, f32x16& p1, float alpha, float& l_reg, bf16x8& pa0, bf16x8& pa1, bf16x8& pa2, bf16x8& pa3) {
; #pragma unroll
;   for (int r = 0; r < 16; ++r) p1[r] = __builtin_amdgcn_exp2f(p1[r]);
;   float ps = 0;
; #pragma unroll
;   for (int r = 0; r < 16; ++r) ps += p0[r];
; #pragma unroll
;   for (int r = 0; r < 16; ++r) ps += p1[r];
;   { auto rr = __builtin_amdgcn_permlane32_swap(__float_as_uint(ps), __float_as_uint(ps), false, false);
;     ps = __uint_as_float(rr[0]) + __uint_as_float(rr[1]); }
;   l_reg = l_reg * alpha + ps;
;     ...
;   PK4(p0, 0, pa0); PK4(p0, 8, pa1); PK4(p1, 0, pa2); PK4(p1, 8, pa3);
;     ...
; }
; template <int DQK> __device__ __forceinline__ void qkt(f32x16& p0, f32x16& p1, const char* Ks, const bf16x8* qr, int r32, int hi) {
;   p0 = f32x16{}; p1 = f32x16{};
; #pragma unroll
;   for (int d0 = 0; d0 < DQK / 16; ++d0) { int cb = (d0 * 16 + hi * 8) * 2;
;     bf16x8 b0 = *reinterpret_cast<const bf16x8*>(Ks + KSWZ(r32, cb));
;     bf16x8 b1 = *reinterpret_cast<const bf16x8*>(Ks + KSWZ(32 + r32, cb));
;     p0 = __builtin_amdgcn_mfma_f32_32x32x16_bf16(b0, qr[d0], p0, 0, 0, 0);
;     p1 = __builtin_amdgcn_mfma_f32_32x32x16_bf16(b1, qr[d0], p1, 0, 0, 0); }
; }
; __device__ __forceinline__ int v_st(int k, int c) { const int kk = (k & ~0xC) | ((k & 4) << 1) | ((k & 8) >> 1); return ((kk >> 3) * 4 + (c >> 5)) * 512 + ((kk & 7) * 32 + (c & 31)) * 2; }
; __device__ __forceinline__ int v_rd_base(int lane) { return ((lane & 3) << 3) | (((lane >> 2) & 3) << 6) | (((lane >> 4) & 1) << 5) | (((lane >> 5) & 1) << 8); }
; template <int OFF> __device__ __forceinline__ s16x4 tr_read(int vb) {
;   s16x4 r; asm volatile("ds_read_b64_tr_b16 %0, %1 offset:%2" : "=&v"(r) : "v"(vb), "i"(OFF) : "memory"); return r;
; }
; template <int D0> __device__ __forceinline__ void pv_one(f32x16& od, int vb, bf16x8 pa0, bf16x8 pa1, bf16x8 pa2, bf16x8 pa3) {
;   const s16x4 l0 = tr_read<v_rd_off(D0, 0, 0)>(vb), h0 = tr_read<v_rd_off(D0, 0, 1)>(vb), l1 = tr_read<v_rd_off(D0, 1, 0)>(vb), h1 = tr_read<v_rd_off(D0, 1, 1)>(vb);
;   const s16x4 l2 = tr_read<v_rd_off(D0, 2, 0)>(vb), h2 = tr_read<v_rd_off(D0, 2, 1)>(vb), l3 = tr_read<v_rd_off(D0, 3, 0)>(vb), h3 = tr_read<v_rd_off(D0, 3, 1)>(vb);
;   asm volatile("s_waitcnt lgkmcnt(0)" ::: "memory"); SBAR();
;   od = __builtin_amdgcn_mfma_f32_32x32x16_bf16(pa0, PKLH(l0, h0), od, 0, 0, 0);
.Lmy_h1B:
	s_waitcnt vmcnt(0)
	ds_write_b128 v146, v[88:91] offset:32768
	ds_write_b128 v145, v[92:95] offset:16384
	v_cvt_pk_bf16_f32 v200, v126, v160
	v_cvt_pk_bf16_f32 v201, v127, v161
	v_cvt_pk_bf16_f32 v202, v158, v162
	v_cvt_pk_bf16_f32 v203, v159, v163
	v_cvt_pk_bf16_f32 v226, v118, v121
	v_cvt_pk_bf16_f32 v227, v119, v122
	v_cvt_pk_bf16_f32 v228, v120, v123
	v_cvt_pk_bf16_f32 v229, v124, v125
	v_cvt_pk_bf16_f32 v230, v114, v115
	v_cvt_pk_bf16_f32 v231, v112, v113
	v_cvt_pk_bf16_f32 v232, v108, v109
	v_cvt_pk_bf16_f32 v233, v104, v105
	v_cvt_pk_bf16_f32 v136, v102, v103
	v_cvt_pk_bf16_f32 v137, v110, v111
	v_cvt_pk_bf16_f32 v138, v106, v107
	v_cvt_pk_bf16_f32 v139, v100, v101
	ds_read_b64_tr_b16 v[184:185], v144 offset:0
	ds_read_b64_tr_b16 v[186:187], v144 offset:0x800
	ds_read_b64_tr_b16 v[188:189], v144 offset:0x1000
	ds_read_b64_tr_b16 v[190:191], v144 offset:0x1800
	ds_read_b64_tr_b16 v[192:193], v144 offset:0x2000
	ds_read_b64_tr_b16 v[194:195], v144 offset:0x2800
	ds_read_b64_tr_b16 v[196:197], v144 offset:0x3000
	ds_read_b64_tr_b16 v[198:199], v144 offset:0x3800
	s_waitcnt lgkmcnt(0)
	s_nop 0
	v_mfma_f32_32x32x16_bf16 v[0:15], v[200:203], v[184:187], v[0:15]
	ds_read_b64_tr_b16 v[184:185], v144 offset:0x200
	ds_read_b64_tr_b16 v[186:187], v144 offset:0xa00
	v_add_f32_e32 v155, v126, v160
	v_add_f32_e32 v155, v127, v155
	v_add_f32_e32 v155, v161, v155
	v_add_f32_e32 v155, v158, v155
	v_mfma_f32_32x32x16_bf16 v[0:15], v[226:229], v[188:191], v[0:15]
	ds_read_b64_tr_b16 v[188:189], v144 offset:0x1200
	ds_read_b64_tr_b16 v[190:191], v144 offset:0x1a00
	v_add_f32_e32 v155, v162, v155
	v_add_f32_e32 v155, v159, v155
	v_add_f32_e32 v155, v163, v155
	v_add_f32_e32 v155, v118, v155
	v_mfma_f32_32x32x16_bf16 v[0:15], v[230:233], v[192:195], v[0:15]
	ds_read_b64_tr_b16 v[192:193], v144 offset:0x2200
	ds_read_b64_tr_b16 v[194:195], v144 offset:0x2a00
	v_add_f32_e32 v155, v121, v155
	v_add_f32_e32 v155, v119, v155
	v_add_f32_e32 v155, v122, v155
	v_add_f32_e32 v155, v120, v155
	v_mfma_f32_32x32x16_bf16 v[0:15], v[136:139], v[196:199], v[0:15]
	ds_read_b64_tr_b16 v[196:197], v144 offset:0x3200
	ds_read_b64_tr_b16 v[198:199], v144 offset:0x3a00
	v_add_f32_e32 v155, v123, v155
	v_add_f32_e32 v155, v124, v155
	v_add_f32_e32 v155, v125, v155
	v_add_f32_e32 v155, v114, v155
	s_waitcnt lgkmcnt(0)
	v_mfma_f32_32x32x16_bf16 v[16:31], v[200:203], v[184:187], v[16:31]
	v_add_f32_e32 v155, v115, v155
	v_add_f32_e32 v155, v112, v155
	v_add_f32_e32 v155, v113, v155
	v_add_f32_e32 v155, v108, v155
	v_mfma_f32_32x32x16_bf16 v[16:31], v[226:229], v[188:191], v[16:31]
	v_add_f32_e32 v155, v109, v155
	v_add_f32_e32 v155, v104, v155
	v_add_f32_e32 v155, v105, v155
	v_add_f32_e32 v155, v102, v155
	v_mfma_f32_32x32x16_bf16 v[16:31], v[230:233], v[192:195], v[16:31]
	v_add_f32_e32 v155, v103, v155
	v_add_f32_e32 v155, v110, v155
	v_add_f32_e32 v155, v111, v155
	v_add_f32_e32 v155, v106, v155
	v_mfma_f32_32x32x16_bf16 v[16:31], v[136:139], v[196:199], v[16:31]
	v_add_f32_e32 v155, v107, v155
	v_add_f32_e32 v155, v100, v155
	v_add_f32_e32 v155, v101, v155
	s_lshl_b32 s0, s11, 6
	s_cmpk_lt_u32 s25, 0x7e
	s_cselect_b32 s1, s10, s24
	s_add_i32 s1, s1, s0
	s_addk_i32 s1, 0xffc0
	s_mul_i32 s1, s1, 0x300
	s_add_u32 s12, s18, s1
	s_addc_u32 s13, s19, 0
	s_cmpk_lt_u32 s25, 0x7f
	s_cselect_b32 s98, s10, s24
	s_add_i32 s98, s98, s0
	s_addk_i32 s98, 0xff80
	s_lshl_b32 s98, s98, 9
	s_add_u32 s98, s20, s98
	s_addc_u32 s99, s21, 0
	global_load_dwordx4 v[100:103], v134, s[12:13]
	global_load_dwordx4 v[108:111], v135, s[98:99]
	ds_read_b128 v[32:35], v148 offset:49152
	ds_read_b128 v[36:39], v148 offset:57344
	ds_read_b128 v[164:167], v152 offset:49152
	ds_read_b128 v[168:171], v152 offset:57344
	s_waitcnt lgkmcnt(3)
	v_mfma_f32_32x32x16_bf16 v[48:63], v[32:35], v[84:87], v[210:225]
	s_waitcnt lgkmcnt(2)
	v_mfma_f32_32x32x16_bf16 v[32:47], v[36:39], v[84:87], v[210:225]
	s_waitcnt lgkmcnt(1)
	v_mfma_f32_32x32x16_bf16 v[48:63], v[164:167], v[80:83], v[48:63]
	s_waitcnt lgkmcnt(0)
	v_mfma_f32_32x32x16_bf16 v[32:47], v[168:171], v[80:83], v[32:47]
	ds_read_b128 v[164:167], v151 offset:49152
	ds_read_b128 v[168:171], v151 offset:57344
	s_waitcnt lgkmcnt(1)
	v_mfma_f32_32x32x16_bf16 v[48:63], v[164:167], v[76:79], v[48:63]
	s_waitcnt lgkmcnt(0)
	v_mfma_f32_32x32x16_bf16 v[32:47], v[168:171], v[76:79], v[32:47]
	ds_read_b128 v[164:167], v149 offset:49152
	ds_read_b128 v[168:171], v149 offset:57344
	s_waitcnt lgkmcnt(1)
	v_mfma_f32_32x32x16_bf16 v[48:63], v[164:167], v[72:75], v[48:63]
	s_waitcnt lgkmcnt(0)
	v_mfma_f32_32x32x16_bf16 v[32:47], v[168:171], v[72:75], v[32:47]
	ds_read_b128 v[164:167], v150 offset:49152
	ds_read_b128 v[168:171], v150 offset:57344
	s_waitcnt lgkmcnt(1)
	v_mfma_f32_32x32x16_bf16 v[48:63], v[164:167], v[68:71], v[48:63]
	s_waitcnt lgkmcnt(0)
	v_mfma_f32_32x32x16_bf16 v[32:47], v[168:171], v[68:71], v[32:47]
	ds_read_b128 v[164:167], v153 offset:49152
	ds_read_b128 v[168:171], v153 offset:57344
	s_waitcnt lgkmcnt(1)
	v_mfma_f32_32x32x16_bf16 v[48:63], v[164:167], v[64:67], v[48:63]
	s_waitcnt lgkmcnt(0)
	v_mfma_f32_32x32x16_bf16 v[32:47], v[168:171], v[64:67], v[32:47]
	s_nop 7
	s_nop 4
	v_max_f32_e32 v112, v48, v49
	v_max3_f32 v112, v112, v50, v51
	v_max3_f32 v112, v112, v52, v53
	v_max3_f32 v112, v112, v54, v55
	v_max3_f32 v112, v112, v56, v57
	v_max3_f32 v112, v112, v58, v59
	v_max3_f32 v112, v112, v60, v61
	v_max3_f32 v112, v112, v62, v63
	v_max3_f32 v112, v112, v32, v33
	v_max3_f32 v112, v112, v34, v35
	v_max3_f32 v112, v112, v36, v37
	v_max3_f32 v112, v112, v38, v39
	v_max3_f32 v112, v112, v40, v41
	v_max3_f32 v112, v112, v42, v43
	v_max3_f32 v112, v112, v44, v45
	v_max3_f32 v112, v112, v46, v47
	v_cmp_ge_f32_e32 vcc, s80, v112
	s_cmp_eq_u64 vcc, exec
	s_cbranch_scc0 .Lmy_rare_b1
	v_mov_b32_e32 v157, 1.0
	s_mov_b64 vcc, 0

; __device__ __forceinline__ void finishSM(f32x16& p0, f32x16& p1, float alpha, float& l_reg, bf16x8& pa0, bf16x8& pa1, bf16x8& pa2, bf16x8& pa3) {
; #pragma unroll
;   for (int r = 0; r < 16; ++r) p1[r] = __builtin_amdgcn_exp2f(p1[r]);
;   float ps = 0;
; #pragma unroll
;   for (int r = 0; r < 16; ++r) ps += p0[r];
; #pragma unroll
;   for (int r = 0; r < 16; ++r) ps += p1[r];
;   { auto rr = __builtin_amdgcn_permlane32_swap(__float_as_uint(ps), __float_as_uint(ps), false, false);
;     ps = __uint_as_float(rr[0]) + __uint_as_float(rr[1]); }
;   l_reg = l_reg * alpha + ps;
;     ...
;   PK4(p0, 0, pa0); PK4(p0, 8, pa1); PK4(p1, 0, pa2); PK4(p1, 8, pa3);
;     ...
; }
; template <int DQK> __device__ __forceinline__ void qkt(f32x16& p0, f32x16& p1, const char* Ks, const bf16x8* qr, int r32, int hi) {
;   p0 = f32x16{}; p1 = f32x16{};
; #pragma unroll
;   for (int d0 = 0; d0 < DQK / 16; ++d0) { int cb = (d0 * 16 + hi * 8) * 2;
;     bf16x8 b0 = *reinterpret_cast<const bf16x8*>(Ks + KSWZ(r32, cb));
;     bf16x8 b1 = *reinterpret_cast<const bf16x8*>(Ks + KSWZ(32 + r32, cb));
;     p0 = __builtin_amdgcn_mfma_f32_32x32x16_bf16(b0, qr[d0], p0, 0, 0, 0);
;     p1 = __builtin_amdgcn_mfma_f32_32x32x16_bf16(b1, qr[d0], p1, 0, 0, 0); }
; }
; __device__ __forceinline__ int v_st(int k, int c) { const int kk = (k & ~0xC) | ((k & 4) << 1) | ((k & 8) >> 1); return ((kk >> 3) * 4 + (c >> 5)) * 512 + ((kk & 7) * 32 + (c & 31)) * 2; }
; __device__ __forceinline__ int v_rd_base(int lane) { return ((lane & 3) << 3) | (((lane >> 2) & 3) << 6) | (((lane >> 4) & 1) << 5) | (((lane >> 5) & 1) << 8); }
; template <int OFF> __device__ __forceinline__ s16x4 tr_read(int vb) {
;   s16x4 r; asm volatile("ds_read_b64_tr_b16 %0, %1 offset:%2" : "=&v"(r) : "v"(vb), "i"(OFF) : "memory"); return r;
; }
; template <int D0> __device__ __forceinline__ void pv_one(f32x16& od, int vb, bf16x8 pa0, bf16x8 pa1, bf16x8 pa2, bf16x8 pa3) {
;   const s16x4 l0 = tr_read<v_rd_off(D0, 0, 0)>(vb), h0 = tr_read<v_rd_off(D0, 0, 1)>(vb), l1 = tr_read<v_rd_off(D0, 1, 0)>(vb), h1 = tr_read<v_rd_off(D0, 1, 1)>(vb);
;   const s16x4 l2 = tr_read<v_rd_off(D0, 2, 0)>(vb), h2 = tr_read<v_rd_off(D0, 2, 1)>(vb), l3 = tr_read<v_rd_off(D0, 3, 0)>(vb), h3 = tr_read<v_rd_off(D0, 3, 1)>(vb);
;   asm volatile("s_waitcnt lgkmcnt(0)" ::: "memory"); SBAR();
;   od = __builtin_amdgcn_mfma_f32_32x32x16_bf16(pa0, PKLH(l0, h0), od, 0, 0, 0);
.Lmy_h1B_304:
	s_waitcnt lgkmcnt(0)
	s_barrier
	s_waitcnt vmcnt(0)
	ds_write_b128 v146, v[100:103] offset:49152
	ds_write_b128 v145, v[108:111]
	v_cvt_pk_bf16_f32 v200, v112, v127
	v_cvt_pk_bf16_f32 v201, v113, v126
	v_cvt_pk_bf16_f32 v202, v114, v125
	v_cvt_pk_bf16_f32 v203, v115, v124
	v_cvt_pk_bf16_f32 v226, v116, v123
	v_cvt_pk_bf16_f32 v227, v117, v122
	v_cvt_pk_bf16_f32 v228, v118, v121
	v_cvt_pk_bf16_f32 v229, v119, v120
	v_cvt_pk_bf16_f32 v230, v167, v168
	v_cvt_pk_bf16_f32 v231, v169, v170
	v_cvt_pk_bf16_f32 v232, v171, v172
	v_cvt_pk_bf16_f32 v233, v160, v161
	v_cvt_pk_bf16_f32 v136, v162, v163
	v_cvt_pk_bf16_f32 v137, v164, v165
	v_cvt_pk_bf16_f32 v138, v166, v173
	v_cvt_pk_bf16_f32 v139, v174, v159
	ds_read_b64_tr_b16 v[184:185], v143 offset:0
	ds_read_b64_tr_b16 v[186:187], v143 offset:0x800
	ds_read_b64_tr_b16 v[188:189], v143 offset:0x1000
	ds_read_b64_tr_b16 v[190:191], v143 offset:0x1800
	ds_read_b64_tr_b16 v[192:193], v143 offset:0x2000
	ds_read_b64_tr_b16 v[194:195], v143 offset:0x2800
	ds_read_b64_tr_b16 v[196:197], v143 offset:0x3000
	ds_read_b64_tr_b16 v[198:199], v143 offset:0x3800
	s_waitcnt lgkmcnt(0)
	s_nop 0
	v_mfma_f32_32x32x16_bf16 v[0:15], v[200:203], v[184:187], v[0:15]
	ds_read_b64_tr_b16 v[184:185], v143 offset:0x200
	ds_read_b64_tr_b16 v[186:187], v143 offset:0xa00
	v_add_f32_e32 v156, v112, v127
	v_add_f32_e32 v156, v113, v156
	v_add_f32_e32 v156, v126, v156
	v_add_f32_e32 v156, v114, v156
	v_mfma_f32_32x32x16_bf16 v[0:15], v[226:229], v[188:191], v[0:15]
	ds_read_b64_tr_b16 v[188:189], v143 offset:0x1200
	ds_read_b64_tr_b16 v[190:191], v143 offset:0x1a00
	v_add_f32_e32 v156, v125, v156
	v_add_f32_e32 v156, v115, v156
	v_add_f32_e32 v156, v124, v156
	v_add_f32_e32 v156, v116, v156
	v_mfma_f32_32x32x16_bf16 v[0:15], v[230:233], v[192:195], v[0:15]
	ds_read_b64_tr_b16 v[192:193], v143 offset:0x2200
	ds_read_b64_tr_b16 v[194:195], v143 offset:0x2a00
	v_add_f32_e32 v156, v123, v156
	v_add_f32_e32 v156, v117, v156
	v_add_f32_e32 v156, v122, v156
	v_add_f32_e32 v156, v118, v156
	v_mfma_f32_32x32x16_bf16 v[0:15], v[136:139], v[196:199], v[0:15]
	ds_read_b64_tr_b16 v[196:197], v143 offset:0x3200
	ds_read_b64_tr_b16 v[198:199], v143 offset:0x3a00
	v_add_f32_e32 v156, v121, v156
	v_add_f32_e32 v156, v119, v156
	v_add_f32_e32 v156, v120, v156
	v_add_f32_e32 v156, v167, v156
	s_waitcnt lgkmcnt(0)
	v_mfma_f32_32x32x16_bf16 v[16:31], v[200:203], v[184:187], v[16:31]
	v_add_f32_e32 v156, v168, v156
	v_add_f32_e32 v156, v169, v156
	v_add_f32_e32 v156, v170, v156
	v_add_f32_e32 v156, v171, v156
	v_mfma_f32_32x32x16_bf16 v[16:31], v[226:229], v[188:191], v[16:31]
	v_add_f32_e32 v156, v172, v156
	v_add_f32_e32 v156, v160, v156
	v_add_f32_e32 v156, v161, v156
	v_add_f32_e32 v156, v162, v156
	v_mfma_f32_32x32x16_bf16 v[16:31], v[230:233], v[192:195], v[16:31]
	v_add_f32_e32 v156, v163, v156
	v_add_f32_e32 v156, v164, v156
	v_add_f32_e32 v156, v165, v156
	v_add_f32_e32 v156, v166, v156
	v_mfma_f32_32x32x16_bf16 v[16:31], v[136:139], v[196:199], v[16:31]
	v_add_f32_e32 v156, v173, v156
	v_add_f32_e32 v156, v174, v156
	v_add_f32_e32 v156, v159, v156
	s_lshl_b32 s0, s11, 6
	s_cmpk_lt_u32 s25, 0x7e
	s_cselect_b32 s98, s10, s24
	s_add_i32 s98, s98, s0
	s_addk_i32 s98, 0xffc0
	s_lshl_b32 s98, s98, 9
	s_add_u32 s98, s20, s98
	s_addc_u32 s99, s21, 0
	global_load_dwordx4 v[92:95], v135, s[98:99]
	s_cmpk_gt_u32 s25, 0x80
	s_cbranch_scc1 .Lmy_h2B_306
	s_cmpk_lt_u32 s25, 0x7d
	s_cselect_b32 s1, s10, s24
	s_add_i32 s1, s1, s0
	s_mul_i32 s1, s1, 0x300
	s_add_u32 s12, s18, s1
	s_addc_u32 s13, s19, 0
	global_load_dwordx4 v[88:91], v134, s[12:13]
.Lmy_h2B_306:
	ds_read_b128 v[32:35], v148 offset:32768
	ds_read_b128 v[36:39], v148 offset:40960
	ds_read_b128 v[176:179], v152 offset:32768
	ds_read_b128 v[180:183], v152 offset:40960
	s_waitcnt lgkmcnt(3)
	v_mfma_f32_32x32x16_bf16 v[48:63], v[32:35], v[84:87], v[210:225]
	s_waitcnt lgkmcnt(2)
	v_mfma_f32_32x32x16_bf16 v[32:47], v[36:39], v[84:87], v[210:225]
	s_waitcnt lgkmcnt(1)
	v_mfma_f32_32x32x16_bf16 v[48:63], v[176:179], v[80:83], v[48:63]
	s_waitcnt lgkmcnt(0)
	v_mfma_f32_32x32x16_bf16 v[32:47], v[180:183], v[80:83], v[32:47]
	ds_read_b128 v[176:179], v151 offset:32768
	ds_read_b128 v[180:183], v151 offset:40960
	s_waitcnt lgkmcnt(1)
	v_mfma_f32_32x32x16_bf16 v[48:63], v[176:179], v[76:79], v[48:63]
	s_waitcnt lgkmcnt(0)
	v_mfma_f32_32x32x16_bf16 v[32:47], v[180:183], v[76:79], v[32:47]
	ds_read_b128 v[176:179], v149 offset:32768
	ds_read_b128 v[180:183], v149 offset:40960
	s_waitcnt lgkmcnt(1)
	v_mfma_f32_32x32x16_bf16 v[48:63], v[176:179], v[72:75], v[48:63]
	s_waitcnt lgkmcnt(0)
	v_mfma_f32_32x32x16_bf16 v[32:47], v[180:183], v[72:75], v[32:47]
	ds_read_b128 v[176:179], v150 offset:32768
	ds_read_b128 v[180:183], v150 offset:40960
	s_waitcnt lgkmcnt(1)
	v_mfma_f32_32x32x16_bf16 v[48:63], v[176:179], v[68:71], v[48:63]
	s_waitcnt lgkmcnt(0)
	v_mfma_f32_32x32x16_bf16 v[32:47], v[180:183], v[68:71], v[32:47]
	ds_read_b128 v[176:179], v153 offset:32768
	ds_read_b128 v[180:183], v153 offset:40960
	s_waitcnt lgkmcnt(1)
	v_mfma_f32_32x32x16_bf16 v[48:63], v[176:179], v[64:67], v[48:63]
	s_waitcnt lgkmcnt(0)
	v_mfma_f32_32x32x16_bf16 v[32:47], v[180:183], v[64:67], v[32:47]
	s_nop 7
	s_nop 4
	v_max_f32_e32 v112, v48, v49
	v_max3_f32 v112, v112, v50, v51
	v_max3_f32 v112, v112, v52, v53
	v_max3_f32 v112, v112, v54, v55
	v_max3_f32 v112, v112, v56, v57
	v_max3_f32 v112, v112, v58, v59
	v_max3_f32 v112, v112, v60, v61
	v_max3_f32 v112, v112, v62, v63
	v_max3_f32 v112, v112, v32, v33
	v_max3_f32 v112, v112, v34, v35
	v_max3_f32 v112, v112, v36, v37
	v_max3_f32 v112, v112, v38, v39
	v_max3_f32 v112, v112, v40, v41
	v_max3_f32 v112, v112, v42, v43
	v_max3_f32 v112, v112, v44, v45
	v_max3_f32 v112, v112, v46, v47
	v_cmp_ge_f32_e32 vcc, s80, v112
	s_cmp_eq_u64 vcc, exec
	s_cbranch_scc0 .Lmy_rare_b2
	v_mov_b32_e32 v117, 1.0
	s_mov_b64 vcc, 0
